# zero-operand MFMA accumulator clear combined with the sunk re-stagger rendezvous
# speedup vs baseline: 1.0028x; 1.0028x over previous
.LBB0_245:
	s_ashr_i32 s69, s68, 31
	s_lshl_b64 s[56:57], s[68:69], 20
	s_add_u32 s33, s14, s56
	s_addc_u32 s48, s15, s57
	s_ashr_i32 s75, s74, 31
	s_lshl_b64 s[56:57], s[74:75], 7
	s_add_u32 s84, s33, s56
	s_addc_u32 s85, s48, s57
	s_and_b64 s[76:77], s[90:91], exec
	s_cselect_b32 s69, s85, s1
	s_cselect_b32 s75, s84, s0
	s_ashr_i32 s73, s72, 31
	s_lshl_b64 s[76:77], s[72:73], 20
	s_add_u32 s33, s9, s76
	s_addc_u32 s48, s23, s77
	s_add_u32 s86, s33, s56
	s_addc_u32 s87, s48, s57
	s_and_b64 s[56:57], s[90:91], exec
	s_cselect_b32 s73, s87, s89
	s_cselect_b32 vcc_lo, s86, s88
	s_add_i32 vcc_hi, s55, -2
	s_add_u32 s0, s0, 0x80080
	s_addc_u32 s1, s1, 0
	s_add_u32 s56, s88, 0x100
	s_addc_u32 s57, s89, 0
	s_mov_b32 s88, 0
	v_mov_b64_e32 v[222:223], 0
	v_mov_b64_e32 v[224:225], 0
	s_nop 1
	v_mfma_f32_32x32x16_bf16 v[4:19], v[222:225], v[222:225], 0
	v_mfma_f32_32x32x16_bf16 v[20:35], v[222:225], v[222:225], 0
	v_mfma_f32_32x32x16_bf16 v[36:51], v[222:225], v[222:225], 0
	v_mfma_f32_32x32x16_bf16 v[52:67], v[222:225], v[222:225], 0
	v_mfma_f32_32x32x16_bf16 v[68:83], v[222:225], v[222:225], 0
	v_mfma_f32_32x32x16_bf16 v[84:99], v[222:225], v[222:225], 0
	v_mfma_f32_32x32x16_bf16 v[100:115], v[222:225], v[222:225], 0
	v_mfma_f32_32x32x16_bf16 v[116:131], v[222:225], v[222:225], 0
	v_add_u32_e32 v246, 0x10000, v1
	v_add_u32_e32 v247, 0x14000, v1
	v_add_u32_e32 v248, 0x18000, v1
	v_add_u32_e32 v249, 0x1c000, v1
	s_cmp_eq_u32 s100, 0
	s_cbranch_scc1 .Lrs1
	s_barrier
	s_mov_b32 s100, 0

.LBB0_520:
	s_add_i32 s9, s64, -2
	s_add_u32 s74, s74, 0x80080
	s_addc_u32 s75, s75, 0
	s_add_u32 s23, s84, 0x100
	s_addc_u32 s35, s85, 0
	s_mov_b32 s54, 0
	v_mov_b64_e32 v[222:223], 0
	v_mov_b64_e32 v[224:225], 0
	s_nop 1
	v_mfma_f32_32x32x16_bf16 v[4:19], v[222:225], v[222:225], 0
	v_mfma_f32_32x32x16_bf16 v[20:35], v[222:225], v[222:225], 0
	v_mfma_f32_32x32x16_bf16 v[36:51], v[222:225], v[222:225], 0
	v_mfma_f32_32x32x16_bf16 v[52:67], v[222:225], v[222:225], 0
	v_mfma_f32_32x32x16_bf16 v[68:83], v[222:225], v[222:225], 0
	v_mfma_f32_32x32x16_bf16 v[84:99], v[222:225], v[222:225], 0
	v_mfma_f32_32x32x16_bf16 v[100:115], v[222:225], v[222:225], 0
	v_mfma_f32_32x32x16_bf16 v[116:131], v[222:225], v[222:225], 0
	v_add_u32_e32 v246, 0x10000, v142
	v_add_u32_e32 v247, 0x14000, v142
	v_add_u32_e32 v248, 0x18000, v142
	v_add_u32_e32 v249, 0x1c000, v142
	s_cmp_eq_u32 s100, 0
	s_cbranch_scc1 .Lrs3
	s_barrier
	s_mov_b32 s100, 0

.LBB0_693:
	s_ashr_i32 s75, s74, 31
	s_lshl_b64 s[16:17], s[74:75], 20
	s_add_u32 s84, s14, s16
	s_addc_u32 s85, s15, s17
	s_and_b64 s[16:17], s[36:37], exec
	s_cselect_b32 s16, s85, s89
	s_cselect_b32 s17, s84, s88
	s_ashr_i32 s73, s72, 31
	s_lshl_b64 s[50:51], s[72:73], 20
	s_add_u32 s86, s23, s50
	s_addc_u32 s87, s29, s51
	s_and_b64 s[50:51], s[36:37], exec
	s_cselect_b32 s50, s87, s91
	s_cselect_b32 s51, s86, s90
	s_add_u32 s88, s88, 0x80080
	s_addc_u32 s89, s89, 0
	s_add_u32 s54, s90, 0x100
	s_addc_u32 s55, s91, 0
	s_mov_b32 s56, -2
	v_mov_b64_e32 v[222:223], 0
	v_mov_b64_e32 v[224:225], 0
	s_nop 1
	v_mfma_f32_32x32x16_bf16 v[4:19], v[222:225], v[222:225], 0
	v_mfma_f32_32x32x16_bf16 v[20:35], v[222:225], v[222:225], 0
	v_mfma_f32_32x32x16_bf16 v[36:51], v[222:225], v[222:225], 0
	v_mfma_f32_32x32x16_bf16 v[52:67], v[222:225], v[222:225], 0
	v_mfma_f32_32x32x16_bf16 v[68:83], v[222:225], v[222:225], 0
	v_mfma_f32_32x32x16_bf16 v[84:99], v[222:225], v[222:225], 0
	v_mfma_f32_32x32x16_bf16 v[100:115], v[222:225], v[222:225], 0
	v_mfma_f32_32x32x16_bf16 v[116:131], v[222:225], v[222:225], 0
	v_add_u32_e32 v246, 0x10000, v144
	v_add_u32_e32 v247, 0x14000, v144
	v_add_u32_e32 v248, 0x18000, v144
	v_add_u32_e32 v249, 0x1c000, v144
	s_cmp_eq_u32 s100, 0
	s_cbranch_scc1 .Lrs5
	s_barrier
	s_mov_b32 s100, 0

.LBB0_762:
	s_add_i32 s23, s51, -2
	s_add_u32 s84, s84, 0x200080
	s_addc_u32 s85, s85, 0
	s_add_u32 s29, s86, 0x100
	s_addc_u32 s35, s87, 0
	s_mov_b32 s55, 0
	v_mov_b64_e32 v[222:223], 0
	v_mov_b64_e32 v[224:225], 0
	s_nop 1
	v_mfma_f32_32x32x16_bf16 v[4:19], v[222:225], v[222:225], 0
	v_mfma_f32_32x32x16_bf16 v[20:35], v[222:225], v[222:225], 0
	v_mfma_f32_32x32x16_bf16 v[36:51], v[222:225], v[222:225], 0
	v_mfma_f32_32x32x16_bf16 v[52:67], v[222:225], v[222:225], 0
	v_mfma_f32_32x32x16_bf16 v[68:83], v[222:225], v[222:225], 0
	v_mfma_f32_32x32x16_bf16 v[84:99], v[222:225], v[222:225], 0
	v_mfma_f32_32x32x16_bf16 v[100:115], v[222:225], v[222:225], 0
	v_mfma_f32_32x32x16_bf16 v[116:131], v[222:225], v[222:225], 0
	v_add_u32_e32 v246, 0x10000, v142
	v_add_u32_e32 v247, 0x14000, v142
	v_add_u32_e32 v248, 0x18000, v142
	v_add_u32_e32 v249, 0x1c000, v142
	s_cmp_eq_u32 s100, 0
	s_cbranch_scc1 .Lrs6
	s_barrier
	s_mov_b32 s100, 0
